# IN skinny units: the 16 activation rows shared through LDS (each wave DMAs 4 of the 32 k-steps in fragment order) instead of being loaded by all 8 waves
# speedup vs baseline: 1.0148x; 1.0148x over previous
; DI void gemm_in(const Params& p, int l, int bid, int nb, char* smem, const int tid) {
;     ...
;     for (; have; tm = tm2, tn = tn2) {
;         have = ti.next(tm2, tn2);
;         const int m0 = tm * 256, n0 = tn * 128;
;         f32x4 acc[4][4]; zero_acc(acc);
;         gemm_stream(A, 1024, Bt, 1024, 1024, m0, n0, have, tm2 * 256, tn2 * 128, smem, acc, tid, rg);
.Lin_su:
	s_lshr_b32 s93, s55, 4
	s_and_b32 s98, s55, 15
	s_lshl_b32 s1, s93, 15
	s_add_u32 s1, s1, 0x5240000
	s_add_u32 s66, s88, s1
	s_addc_u32 s67, s89, 0
	s_lshl_b32 s1, s98, 18
	s_lshl_b32 s2, s10, 15
	s_add_u32 s1, s1, s2
	s_add_u32 s1, s1, 0x1080000
	s_add_u32 s70, s88, s1
	s_addc_u32 s71, s89, 0
	s_lshl_b32 s1, s10, 8
	s_add_u32 s74, s66, s1
	s_addc_u32 s75, s67, 0
	s_lshl_b32 s1, s10, 12
	s_add_i32 m0, s1, 0x10
	s_nop 0
	global_load_lds_dwordx4 v186, s[74:75]
	s_add_u32 s74, s74, 64
	s_addc_u32 s75, s75, 0
	s_add_i32 m0, s1, 0x410
	s_nop 0
	global_load_lds_dwordx4 v186, s[74:75]
	s_add_u32 s74, s74, 64
	s_addc_u32 s75, s75, 0
	s_add_i32 m0, s1, 0x810
	s_nop 0
	global_load_lds_dwordx4 v186, s[74:75]
	s_add_u32 s74, s74, 64
	s_addc_u32 s75, s75, 0
	s_add_i32 m0, s1, 0xc10
	s_nop 0
	global_load_lds_dwordx4 v186, s[74:75]
	global_load_dwordx4 v[92:95], v186, s[70:71] offset:0
	global_load_dwordx4 v[96:99], v186, s[70:71] offset:64
	global_load_dwordx4 v[100:103], v186, s[70:71] offset:128
	global_load_dwordx4 v[104:107], v186, s[70:71] offset:192
	global_load_dwordx4 v[108:111], v186, s[70:71] offset:256
	global_load_dwordx4 v[112:115], v186, s[70:71] offset:320
	global_load_dwordx4 v[116:119], v186, s[70:71] offset:384
	global_load_dwordx4 v[120:123], v186, s[70:71] offset:448
	global_load_dwordx4 v[124:127], v186, s[70:71] offset:512
	global_load_dwordx4 v[128:131], v186, s[70:71] offset:576
	global_load_dwordx4 v[132:135], v186, s[70:71] offset:640
	global_load_dwordx4 v[136:139], v186, s[70:71] offset:704
	global_load_dwordx4 v[140:143], v186, s[70:71] offset:768
	global_load_dwordx4 v[144:147], v186, s[70:71] offset:832
	global_load_dwordx4 v[148:151], v186, s[70:71] offset:896
	global_load_dwordx4 v[152:155], v186, s[70:71] offset:960
	v_lshlrev_b32_e32 v187, 4, v190
	s_waitcnt vmcnt(16)
	s_barrier
; DI unsigned pk2(float lo, float hi) { const f32x2 v = {lo, hi}; return __builtin_bit_cast(unsigned, __builtin_convertvector(v, bf2_t)); }
; DI void gemm_in(const Params& p, int l, int bid, int nb, char* smem, const int tid) {
;     ...
;         const int nb0 = n0 + wn * 64;
;         const int seg = nb0 >> 8;
;         const int cin = nb0 & 255;
;         if (seg == 0 || seg == 3) {
;             bf16_t* Q = (bf16_t*)(p.ws + (seg == 0 ? B_QA : B_QC));
; #pragma unroll
;             for (int mi = 0; mi < 4; ++mi) {
;                 const int row = m0 + wm * 64 + mi * 16 + r;
; #pragma unroll
;                 for (int ni = 0; ni < 4; ++ni) {
;                     u32x2 w; w.x = pk2(acc[mi][ni][0], acc[mi][ni][1]); w.y = pk2(acc[mi][ni][2], acc[mi][ni][3]);
;                     *(u32x2*)(Q + (size_t)row * 256 + cin + ni * 16 + q * 4) = w;
;                 }
;             }
;         } else if (seg < 6) {
;             const size_t boff = seg == 1 ? B_KA : seg == 2 ? B_VA : seg == 4 ? B_KC : B_VC;
;             const bool samp = m0 >= NP;
;             const size_t ooff = samp ? (seg == 1 ? O_AKS : seg == 2 ? O_AVS : seg == 4 ? O_CKS : O_CVS) : (seg == 1 ? O_AKP : seg == 2 ? O_AVP : seg == 4 ? O_CKP : O_CVP);
;             bf16_t* KV = (bf16_t*)(p.ws + boff);
; #pragma unroll
;             for (int mi = 0; mi < 4; ++mi) {
;                 const int row = m0 + wm * 64 + mi * 16 + r;
;                 const size_t srow = samp ? (size_t)(l * NS + (row - NP)) : (size_t)(l * NP + row);
;                 const size_t kr = (size_t)krow_of(row);
; #pragma unroll
;                 for (int ni = 0; ni < 4; ++ni) {
;                     const int c = cin + ni * 16 + q * 4;
;                     *(f32x4*)(p.out + ooff + srow * 256 + c) = acc[mi][ni];
;                     u32x2 w; w.x = pk2(acc[mi][ni][0], acc[mi][ni][1]); w.y = pk2(acc[mi][ni][2], acc[mi][ni][3]);
;                     *(u32x2*)(KV + kr * 256 + c) = w;
;                 }
;             }
	ds_read_b128 v[28:31], v187 offset:16
	ds_read_b128 v[32:35], v187 offset:1040
	ds_read_b128 v[36:39], v187 offset:2064
	ds_read_b128 v[40:43], v187 offset:3088
	v_mov_b64_e32 v[24:25], 0
	v_mov_b64_e32 v[26:27], 0
	s_waitcnt vmcnt(15) lgkmcnt(3)
	v_mfma_f32_16x16x32_bf16 v[24:27], v[92:95], v[28:31], v[24:27]
	ds_read_b128 v[44:47], v187 offset:4112
	global_load_dwordx4 v[92:95], v186, s[70:71] offset:1024
	s_waitcnt vmcnt(15) lgkmcnt(3)
	v_mfma_f32_16x16x32_bf16 v[24:27], v[96:99], v[32:35], v[24:27]
	ds_read_b128 v[48:51], v187 offset:5136
	global_load_dwordx4 v[96:99], v186, s[70:71] offset:1088
	s_waitcnt vmcnt(15) lgkmcnt(3)
	v_mfma_f32_16x16x32_bf16 v[24:27], v[100:103], v[36:39], v[24:27]
	ds_read_b128 v[52:55], v187 offset:6160
	global_load_dwordx4 v[100:103], v186, s[70:71] offset:1152
	s_waitcnt vmcnt(15) lgkmcnt(3)
	v_mfma_f32_16x16x32_bf16 v[24:27], v[104:107], v[40:43], v[24:27]
	ds_read_b128 v[56:59], v187 offset:7184
	global_load_dwordx4 v[104:107], v186, s[70:71] offset:1216
	s_waitcnt vmcnt(15) lgkmcnt(3)
	v_mfma_f32_16x16x32_bf16 v[24:27], v[108:111], v[44:47], v[24:27]
	ds_read_b128 v[60:63], v187 offset:8208
	global_load_dwordx4 v[108:111], v186, s[70:71] offset:1280
	s_waitcnt vmcnt(15) lgkmcnt(3)
	v_mfma_f32_16x16x32_bf16 v[24:27], v[112:115], v[48:51], v[24:27]
	ds_read_b128 v[64:67], v187 offset:9232
	global_load_dwordx4 v[112:115], v186, s[70:71] offset:1344
	s_waitcnt vmcnt(15) lgkmcnt(3)
	v_mfma_f32_16x16x32_bf16 v[24:27], v[116:119], v[52:55], v[24:27]
	ds_read_b128 v[68:71], v187 offset:10256
	global_load_dwordx4 v[116:119], v186, s[70:71] offset:1408
	s_waitcnt vmcnt(15) lgkmcnt(3)
	v_mfma_f32_16x16x32_bf16 v[24:27], v[120:123], v[56:59], v[24:27]
	ds_read_b128 v[72:75], v187 offset:11280
	global_load_dwordx4 v[120:123], v186, s[70:71] offset:1472
	s_waitcnt vmcnt(15) lgkmcnt(3)
	v_mfma_f32_16x16x32_bf16 v[24:27], v[124:127], v[60:63], v[24:27]
	ds_read_b128 v[76:79], v187 offset:12304
	global_load_dwordx4 v[124:127], v186, s[70:71] offset:1536
	s_waitcnt vmcnt(15) lgkmcnt(3)
	v_mfma_f32_16x16x32_bf16 v[24:27], v[128:131], v[64:67], v[24:27]
	ds_read_b128 v[80:83], v187 offset:13328
	global_load_dwordx4 v[128:131], v186, s[70:71] offset:1600
	s_waitcnt vmcnt(15) lgkmcnt(3)
	v_mfma_f32_16x16x32_bf16 v[24:27], v[132:135], v[68:71], v[24:27]
	ds_read_b128 v[84:87], v187 offset:14352
	global_load_dwordx4 v[132:135], v186, s[70:71] offset:1664
	s_waitcnt vmcnt(15) lgkmcnt(3)
	v_mfma_f32_16x16x32_bf16 v[24:27], v[136:139], v[72:75], v[24:27]
	ds_read_b128 v[88:91], v187 offset:15376
	global_load_dwordx4 v[136:139], v186, s[70:71] offset:1728
	s_waitcnt vmcnt(15) lgkmcnt(3)
	v_mfma_f32_16x16x32_bf16 v[24:27], v[140:143], v[76:79], v[24:27]
	ds_read_b128 v[28:31], v187 offset:16400
	global_load_dwordx4 v[140:143], v186, s[70:71] offset:1792
	s_waitcnt vmcnt(15) lgkmcnt(3)
	v_mfma_f32_16x16x32_bf16 v[24:27], v[144:147], v[80:83], v[24:27]
	ds_read_b128 v[32:35], v187 offset:17424
	global_load_dwordx4 v[144:147], v186, s[70:71] offset:1856
	s_waitcnt vmcnt(15) lgkmcnt(3)
	v_mfma_f32_16x16x32_bf16 v[24:27], v[148:151], v[84:87], v[24:27]
	ds_read_b128 v[36:39], v187 offset:18448
	global_load_dwordx4 v[148:151], v186, s[70:71] offset:1920
	s_waitcnt vmcnt(15) lgkmcnt(3)
	v_mfma_f32_16x16x32_bf16 v[24:27], v[152:155], v[88:91], v[24:27]
	ds_read_b128 v[40:43], v187 offset:19472
	global_load_dwordx4 v[152:155], v186, s[70:71] offset:1984
	s_waitcnt vmcnt(15) lgkmcnt(3)
	v_mfma_f32_16x16x32_bf16 v[24:27], v[92:95], v[28:31], v[24:27]
	ds_read_b128 v[44:47], v187 offset:20496
	s_waitcnt vmcnt(14) lgkmcnt(3)
	v_mfma_f32_16x16x32_bf16 v[24:27], v[96:99], v[32:35], v[24:27]
	ds_read_b128 v[48:51], v187 offset:21520
	s_waitcnt vmcnt(13) lgkmcnt(3)
	v_mfma_f32_16x16x32_bf16 v[24:27], v[100:103], v[36:39], v[24:27]
	ds_read_b128 v[52:55], v187 offset:22544
	s_waitcnt vmcnt(12) lgkmcnt(3)
	v_mfma_f32_16x16x32_bf16 v[24:27], v[104:107], v[40:43], v[24:27]
	ds_read_b128 v[56:59], v187 offset:23568
	s_waitcnt vmcnt(11) lgkmcnt(3)
	v_mfma_f32_16x16x32_bf16 v[24:27], v[108:111], v[44:47], v[24:27]
	ds_read_b128 v[60:63], v187 offset:24592
	s_waitcnt vmcnt(10) lgkmcnt(3)
	v_mfma_f32_16x16x32_bf16 v[24:27], v[112:115], v[48:51], v[24:27]
	ds_read_b128 v[64:67], v187 offset:25616
	s_waitcnt vmcnt(9) lgkmcnt(3)
	v_mfma_f32_16x16x32_bf16 v[24:27], v[116:119], v[52:55], v[24:27]
	ds_read_b128 v[68:71], v187 offset:26640
	s_waitcnt vmcnt(8) lgkmcnt(3)
	v_mfma_f32_16x16x32_bf16 v[24:27], v[120:123], v[56:59], v[24:27]
	ds_read_b128 v[72:75], v187 offset:27664
	s_waitcnt vmcnt(7) lgkmcnt(3)
	v_mfma_f32_16x16x32_bf16 v[24:27], v[124:127], v[60:63], v[24:27]
	ds_read_b128 v[76:79], v187 offset:28688
	s_waitcnt vmcnt(6) lgkmcnt(3)
	v_mfma_f32_16x16x32_bf16 v[24:27], v[128:131], v[64:67], v[24:27]
	ds_read_b128 v[80:83], v187 offset:29712
	s_waitcnt vmcnt(5) lgkmcnt(3)
	v_mfma_f32_16x16x32_bf16 v[24:27], v[132:135], v[68:71], v[24:27]
	ds_read_b128 v[84:87], v187 offset:30736
	s_waitcnt vmcnt(4) lgkmcnt(3)
	v_mfma_f32_16x16x32_bf16 v[24:27], v[136:139], v[72:75], v[24:27]
	ds_read_b128 v[88:91], v187 offset:31760
	s_waitcnt vmcnt(3) lgkmcnt(3)
	v_mfma_f32_16x16x32_bf16 v[24:27], v[140:143], v[76:79], v[24:27]
	s_waitcnt vmcnt(2) lgkmcnt(2)
	v_mfma_f32_16x16x32_bf16 v[24:27], v[144:147], v[80:83], v[24:27]
	s_waitcnt vmcnt(1) lgkmcnt(1)
	v_mfma_f32_16x16x32_bf16 v[24:27], v[148:151], v[84:87], v[24:27]
	s_waitcnt vmcnt(0) lgkmcnt(0)
	v_mfma_f32_16x16x32_bf16 v[24:27], v[152:155], v[88:91], v[24:27]
	s_lshr_b32 s37, s98, 1
	s_and_b32 s62, s98, 1
	s_lshl_b32 s62, s62, 7
	s_lshl_b32 s1, s10, 4
	s_add_u32 s62, s62, s1
	v_lshlrev_b32_e32 v187, 3, v17
	v_lshl_add_u32 v188, v191, 9, v187
	v_lshlrev_b32_e32 v189, 1, v187
	s_nop 7
	s_nop 7
	s_cmp_eq_u32 s37, 0
	s_cbranch_scc1 .Lin_su_q
	s_cmp_eq_u32 s37, 3
	s_cbranch_scc1 .Lin_su_q
	s_cmp_ge_u32 s37, 6
	s_cbranch_scc1 .Lin_su_sm
	s_mov_b32 s1, 0xd750000
	s_mov_b32 s2, 0x9fc0000
	s_cmp_eq_u32 s37, 4
	s_cselect_b32 s1, 0xd6d0000, s1
	s_cselect_b32 s2, 0x93a0000, s2
	s_cmp_eq_u32 s37, 2
	s_cselect_b32 s1, 0xd600000, s1
	s_cselect_b32 s2, 0x8780000, s2
	s_cmp_eq_u32 s37, 1
	s_cselect_b32 s1, 0xd580000, s1
	s_cselect_b32 s2, 0x7b60000, s2
	v_readlane_b32 s3, v231, 4
	s_lshl_b32 s3, s3, 18
	s_add_u32 s1, s1, s3
	s_lshl_b32 s3, s93, 14
	s_add_u32 s1, s1, s3
	s_lshl_b32 s3, s62, 2
	s_add_u32 s1, s1, s3
	v_readlane_b32 s74, v240, 5
	v_readlane_b32 s75, v240, 6
	s_nop 3
	s_add_u32 s74, s74, s1
	s_addc_u32 s75, s75, 0
	v_lshl_add_u32 v187, v191, 10, v189
	global_store_dwordx4 v187, v[24:27], s[74:75]
	s_lshr_b32 s1, s93, 1
	s_mul_i32 s1, s1, 0x420
	s_and_b32 s3, s93, 1
	s_lshl_b32 s3, s3, 4
	s_add_u32 s1, s1, s3
	s_add_u32 s1, s1, 0x4400
	s_lshl_b32 s1, s1, 9
	s_add_u32 s1, s1, s2
	s_lshl_b32 s3, s62, 1
	s_add_u32 s1, s1, s3
	s_add_u32 s80, s88, s1
	s_addc_u32 s81, s89, 0
	v_cvt_pk_bf16_f32 v28, v24, v25
	v_cvt_pk_bf16_f32 v29, v26, v27
	global_store_dwordx2 v188, v[28:29], s[80:81]
	s_branch .Lin_su_done

; DI void gemm_in(const Params& p, int l, int bid, int nb, char* smem, const int tid) {
;     ...
;         } else {
;             float* SM = (float*)(p.ws + B_SMALL);
; #pragma unroll
;             for (int mi = 0; mi < 4; ++mi) {
;                 const int row = m0 + wm * 64 + mi * 16 + r;
; #pragma unroll
;                 for (int ni = 0; ni < 4; ++ni) *(f32x4*)(SM + (size_t)row * 512 + (nb0 - 1536) + ni * 16 + q * 4) = acc[mi][ni];
;             }
;         }
;     }
.Lin_su_sm:
	s_sub_u32 s1, s37, 6
	s_lshl_b32 s1, s1, 8
	s_add_u32 s1, s1, s62
	s_lshl_b32 s1, s1, 2
	s_lshl_b32 s3, s93, 15
	s_add_u32 s1, s1, s3
	s_add_u32 s1, s1, 0xcc20000
	s_add_u32 s80, s88, s1
	s_addc_u32 s81, s89, 0
	v_lshl_add_u32 v187, v191, 11, v189
	global_store_dwordx4 v187, v[24:27], s[80:81]
.Lin_su_done:
	s_add_u32 s55, s55, s53
	s_cmpk_lt_u32 s55, 0x100
	s_cbranch_scc0 .LBB0_860
	s_barrier
	s_branch .Lin_su
.LBB0_779:
	s_mov_b64 s[0:1], 0
